# baseline (speedup 1.0000x reference)
; __device__ __forceinline__ unsigned pk2(float lo, float hi) { hwf2 v = {lo, hi}; return __builtin_bit_cast(unsigned, __builtin_convertvector(v, hwbf2)); }
; __device__ __forceinline__ float shfl_lane(float x, int src_lane) { return __int_as_float(__builtin_amdgcn_ds_bpermute(src_lane << 2, __float_as_int(x))); }
; template <int EPI> ...
;     ...
;       _Pragma("unroll") for (int ai = 0; ai < 2; ++ai) _Pragma("unroll") for (int mp = 0; mp < 2; ++mp) {
;         float4 rv[2][2][2];
;         _Pragma("unroll") for (int mi = 0; mi < 2; ++mi) _Pragma("unroll") for (int bj = 0; bj < 2; ++bj) _Pragma("unroll") for (int n = 0; n < 2; ++n)
;           rv[mi][bj][n] = *(const float4*)(residf + (size_t)(brow + ai * HALF + wr * 64 + (mp * 2 + mi) * 16 + fr) * DM + (bcol + bj * HALF + wc * 32 + n * 16 + fq * 4));
;         asm volatile("" ::: "memory");
;         _Pragma("unroll") for (int mi = 0; mi < 2; ++mi) {
;           const int m = mp * 2 + mi;
;           const int row = brow + ai * HALF + wr * 64 + m * 16 + fr;
;           float sq = 0.f;
;           const int coff = (fq & 1) ? 16 + (fq - 1) * 4 : fq * 4;
;           _Pragma("unroll") for (int bj = 0; bj < 2; ++bj) {
;             uint2 pk[2];
;             _Pragma("unroll") for (int n = 0; n < 2; ++n) {
;               const float v0 = rv[mi][bj][n].x + acc[ai][bj][m][n][0], v1 = rv[mi][bj][n].y + acc[ai][bj][m][n][1];
;               const float v2 = rv[mi][bj][n].z + acc[ai][bj][m][n][2], v3 = rv[mi][bj][n].w + acc[ai][bj][m][n][3];
;               sq += (v0 * v0 + v1 * v1) + (v2 * v2 + v3 * v3);
;               pk[n].x = pk2(v0, v1); pk[n].y = pk2(v2, v3);
;             }
;             *(uint4*)(outb + pk_off(row, bcol + bj * HALF + wc * 32 + coff)) = widen_pair(pk[0], pk[1]);
;           }
;           sq += shfl_lane(sq, (te_ & 63) ^ 16); sq += shfl_lane(sq, (te_ & 63) ^ 32);
;           if (fq == 0) atomicAdd(ss_out + row, sq);
.LBB0_581:
	v_mov_b32_e32 v0, v166
	s_lshl_b32 s16, s22, 8
	s_lshl_b32 s17, s23, 8
	v_and_b32_e32 v183, 15, v0
	v_ashrrev_i32_e32 v146, 2, v0
	v_and_b32_e32 v120, 0xffffffc0, v146
	v_or_b32_e32 v118, s16, v183
	v_bfe_u32 v119, v0, 4, 2
	v_add_u32_e32 v152, v118, v120
	v_lshrrev_b32_e32 v118, 1, v0
	v_add_u32_e32 v184, s16, v120
	v_and_b32_e32 v120, 16, v0
	v_and_b32_e32 v121, 0x60, v118
	v_lshlrev_b32_e32 v118, 2, v119
	v_cmp_eq_u32_e32 vcc, 0, v120
	v_lshlrev_b32_e32 v120, 3, v119
	v_or3_b32 v118, s17, v118, v121
	v_or_b32_e32 v164, s17, v121
	v_add_u32_e32 v121, 24, v120
	v_cndmask_b32_e32 v186, v121, v120, vcc
	v_cmp_eq_u32_e32 vcc, 0, v119
	v_ashrrev_i32_e32 v119, 31, v118
	v_lshlrev_b64 v[154:155], 2, v[118:119]
	v_or_b32_e32 v118, 16, v152
	v_ashrrev_i32_e32 v153, 31, v152
	v_ashrrev_i32_e32 v119, 31, v118
	v_lshlrev_b64 v[120:121], 14, v[152:153]
	v_lshlrev_b64 v[118:119], 14, v[118:119]
	v_lshl_add_u64 v[120:121], s[0:1], 0, v[120:121]
	v_lshl_add_u64 v[118:119], s[0:1], 0, v[118:119]
	v_lshl_add_u64 v[200:201], v[120:121], 0, v[154:155]
	v_lshl_add_u64 v[118:119], v[118:119], 0, v[154:155]
	global_load_dwordx4 v[130:133], v[118:119], off
	global_load_dwordx4 v[126:129], v[118:119], off offset:64
	global_load_dwordx4 v[122:125], v[118:119], off offset:512
	s_nop 0
	global_load_dwordx4 v[118:121], v[118:119], off offset:576
	v_bfe_u32 v185, v0, 6, 1
	global_load_dwordx4 v[158:161], v[200:201], off
	global_load_dwordx4 v[188:191], v[200:201], off offset:512
	global_load_dwordx4 v[202:205], v[200:201], off offset:64
	global_load_dwordx4 v[206:209], v[200:201], off offset:576
	v_lshrrev_b32_e32 v146, 3, v146
	v_lshlrev_b32_e32 v0, 2, v0
	v_and_or_b32 v146, v146, 8, v185
	v_bitop3_b32 v182, v0, 64, v195 bitop3:0x6c
	v_bitop3_b32 v181, v0, s3, v195 bitop3:0x6c
	v_lshl_or_b32 v147, v183, 6, v186
	v_lshlrev_b32_e32 v187, 10, v146
	v_and_b32_e32 v0, 32, v0
	v_ashrrev_i32_e32 v146, 1, v184
	v_bitop3_b32 v0, v147, v187, v0 bitop3:0xde
	v_and_b32_e32 v199, 0xffffffc0, v146
	v_ashrrev_i32_e32 v153, 6, v164
	v_lshl_add_u64 v[156:157], s[12:13], 0, v[0:1]
	s_waitcnt vmcnt(2)
	v_pk_add_f32 v[142:143], v[142:143], v[158:159]
	v_pk_add_f32 v[144:145], v[144:145], v[160:161]
	v_pk_mul_f32 v[158:159], v[142:143], v[142:143]
	v_pk_mul_f32 v[160:161], v[144:145], v[144:145]
	v_cvt_pk_bf16_f32 v142, v142, v143
	v_cvt_pk_bf16_f32 v143, v144, v145
	v_pk_add_f32 v[134:135], v[134:135], v[188:189]
	v_pk_add_f32 v[188:189], v[136:137], v[190:191]
	v_pk_mul_f32 v[136:137], v[134:135], v[134:135]
	v_pk_mul_f32 v[164:165], v[188:189], v[188:189]
	v_cvt_pk_bf16_f32 v134, v134, v135
	v_cvt_pk_bf16_f32 v135, v188, v189
	v_add_f32_e32 v136, v136, v137
	s_waitcnt vmcnt(0)
	v_pk_add_f32 v[138:139], v[138:139], v[202:203]
	v_pk_add_f32 v[146:147], v[140:141], v[204:205]
	v_pk_mul_f32 v[140:141], v[138:139], v[138:139]
	v_pk_mul_f32 v[162:163], v[146:147], v[146:147]
	v_cvt_pk_bf16_f32 v144, v138, v139
	v_add_u32_e32 v138, v153, v199
	v_add_f32_e32 v0, v162, v163
	v_add_f32_e32 v140, v140, v141
	v_ashrrev_i32_e32 v139, 31, v138
	v_add_f32_e32 v0, v140, v0
	v_add_f32_e32 v140, v160, v161
	v_add_f32_e32 v141, v158, v159
	v_cvt_pk_bf16_f32 v145, v146, v147
	v_lshlrev_b64 v[138:139], 14, v[138:139]
	v_add_f32_e32 v140, v141, v140
	v_lshl_add_u64 v[146:147], v[156:157], 0, v[138:139]
	v_pk_add_f32 v[114:115], v[114:115], v[206:207]
	v_permlane16_swap_b32_e32 v142, v144
	v_permlane16_swap_b32_e32 v143, v145
	v_pk_add_f32 v[116:117], v[116:117], v[208:209]
	v_add_f32_e32 v0, v140, v0
	v_add_f32_e32 v140, v164, v165
	global_store_dwordx4 v[146:147], v[142:145], off
	v_add_f32_e32 v136, v136, v140
	v_add_f32_e32 v0, v0, v136
	v_pk_mul_f32 v[142:143], v[114:115], v[114:115]
	v_pk_mul_f32 v[144:145], v[116:117], v[116:117]
	v_add_f32_e32 v137, v142, v143
	v_add_f32_e32 v136, v144, v145
	v_add_f32_e32 v136, v137, v136
	v_or_b32_e32 v140, 2, v153
	v_add_f32_e32 v0, v0, v136
	v_cvt_pk_bf16_f32 v136, v114, v115
	v_add_u32_e32 v114, v140, v199
	v_ashrrev_i32_e32 v115, 31, v114
	v_cvt_pk_bf16_f32 v137, v116, v117
	v_lshlrev_b64 v[114:115], 14, v[114:115]
	v_permlane16_swap_b32_e32 v134, v136
	v_permlane16_swap_b32_e32 v135, v137
	v_lshl_add_u64 v[116:117], v[156:157], 0, v[114:115]
	global_store_dwordx4 v[116:117], v[134:137], off
	ds_bpermute_b32 v116, v182, v0
	s_waitcnt lgkmcnt(0)
	v_add_f32_e32 v0, v0, v116
	ds_bpermute_b32 v116, v181, v0
	s_and_saveexec_b64 s[16:17], vcc
	s_cbranch_execz .LBB0_583
	v_or_b32_e32 v134, v184, v183
	v_ashrrev_i32_e32 v135, 31, v134
	s_waitcnt lgkmcnt(0)
	v_add_f32_e32 v0, v0, v116
	v_lshl_add_u64 v[116:117], v[134:135], 2, s[14:15]
	global_atomic_add_f32 v[116:117], v0, off

; __device__ __forceinline__ unsigned pk2(float lo, float hi) { hwf2 v = {lo, hi}; return __builtin_bit_cast(unsigned, __builtin_convertvector(v, hwbf2)); }
; __device__ __forceinline__ float shfl_lane(float x, int src_lane) { return __int_as_float(__builtin_amdgcn_ds_bpermute(src_lane << 2, __float_as_int(x))); }
; template <int EPI> ...
;     ...
;       _Pragma("unroll") for (int ai = 0; ai < 2; ++ai) _Pragma("unroll") for (int mp = 0; mp < 2; ++mp) {
;         float4 rv[2][2][2];
;         _Pragma("unroll") for (int mi = 0; mi < 2; ++mi) _Pragma("unroll") for (int bj = 0; bj < 2; ++bj) _Pragma("unroll") for (int n = 0; n < 2; ++n)
;           rv[mi][bj][n] = *(const float4*)(residf + (size_t)(brow + ai * HALF + wr * 64 + (mp * 2 + mi) * 16 + fr) * DM + (bcol + bj * HALF + wc * 32 + n * 16 + fq * 4));
;         asm volatile("" ::: "memory");
;         _Pragma("unroll") for (int mi = 0; mi < 2; ++mi) {
;           const int m = mp * 2 + mi;
;           const int row = brow + ai * HALF + wr * 64 + m * 16 + fr;
;           float sq = 0.f;
;           const int coff = (fq & 1) ? 16 + (fq - 1) * 4 : fq * 4;
;           _Pragma("unroll") for (int bj = 0; bj < 2; ++bj) {
;             uint2 pk[2];
;             _Pragma("unroll") for (int n = 0; n < 2; ++n) {
;               const float v0 = rv[mi][bj][n].x + acc[ai][bj][m][n][0], v1 = rv[mi][bj][n].y + acc[ai][bj][m][n][1];
;               const float v2 = rv[mi][bj][n].z + acc[ai][bj][m][n][2], v3 = rv[mi][bj][n].w + acc[ai][bj][m][n][3];
;               sq += (v0 * v0 + v1 * v1) + (v2 * v2 + v3 * v3);
;               pk[n].x = pk2(v0, v1); pk[n].y = pk2(v2, v3);
;             }
;             *(uint4*)(outb + pk_off(row, bcol + bj * HALF + wc * 32 + coff)) = widen_pair(pk[0], pk[1]);
;           }
;           sq += shfl_lane(sq, (te_ & 63) ^ 16); sq += shfl_lane(sq, (te_ & 63) ^ 32);
;           if (fq == 0) atomicAdd(ss_out + row, sq);
.LBB0_585:
	s_or_b64 exec, exec, s[16:17]
	s_waitcnt lgkmcnt(0)
	v_or_b32_e32 v98, 32, v152
	v_ashrrev_i32_e32 v99, 31, v98
	v_lshlrev_b64 v[98:99], 14, v[98:99]
	v_lshl_add_u64 v[98:99], s[0:1], 0, v[98:99]
	v_lshl_add_u64 v[130:131], v[98:99], 0, v[154:155]
	v_or_b32_e32 v98, 48, v152
	v_ashrrev_i32_e32 v99, 31, v98
	v_lshlrev_b64 v[98:99], 14, v[98:99]
	v_lshl_add_u64 v[98:99], s[0:1], 0, v[98:99]
	v_lshl_add_u64 v[98:99], v[98:99], 0, v[154:155]
	global_load_dwordx4 v[110:113], v[98:99], off
	global_load_dwordx4 v[106:109], v[98:99], off offset:64
	global_load_dwordx4 v[102:105], v[98:99], off offset:512
	s_nop 0
	global_load_dwordx4 v[98:101], v[98:99], off offset:576
	v_or_b32_e32 v0, 32, v184
	global_load_dwordx4 v[120:123], v[130:131], off
	global_load_dwordx4 v[210:213], v[130:131], off offset:64
	global_load_dwordx4 v[214:217], v[130:131], off offset:512
	global_load_dwordx4 v[218:221], v[130:131], off offset:576
	v_or_b32_e32 v116, v0, v183
	v_lshrrev_b32_e32 v0, 3, v0
	v_and_or_b32 v0, v0, 12, v185
	v_lshlrev_b32_e32 v117, 6, v116
	v_lshlrev_b32_e32 v118, 2, v116
	v_and_or_b32 v117, v117, s47, v186
	v_lshlrev_b32_e32 v0, 10, v0
	v_and_b32_e32 v118, 32, v118
	v_bitop3_b32 v0, v117, v0, v118 bitop3:0xde
	v_lshl_add_u64 v[118:119], s[12:13], 0, v[0:1]
	v_lshl_add_u64 v[132:133], v[118:119], 0, v[138:139]
	s_waitcnt vmcnt(3)
	v_pk_add_f32 v[124:125], v[96:97], v[122:123]
	s_nop 0
	v_pk_mul_f32 v[96:97], v[124:125], v[124:125]
	v_cvt_pk_bf16_f32 v123, v124, v125
	v_pk_add_f32 v[120:121], v[94:95], v[120:121]
	s_waitcnt vmcnt(2)
	v_pk_add_f32 v[126:127], v[92:93], v[212:213]
	v_pk_mul_f32 v[94:95], v[120:121], v[120:121]
	v_cvt_pk_bf16_f32 v122, v120, v121
	v_pk_add_f32 v[120:121], v[90:91], v[210:211]
	v_pk_mul_f32 v[92:93], v[126:127], v[126:127]
	v_cvt_pk_bf16_f32 v125, v126, v127
	v_pk_mul_f32 v[90:91], v[120:121], v[120:121]
	v_cvt_pk_bf16_f32 v124, v120, v121
	v_add_f32_e32 v0, v92, v93
	v_add_f32_e32 v90, v90, v91
	v_add_f32_e32 v0, v90, v0
	v_add_f32_e32 v90, v96, v97
	v_add_f32_e32 v91, v94, v95
	v_add_f32_e32 v90, v91, v90
	v_permlane16_swap_b32_e32 v122, v124
	v_permlane16_swap_b32_e32 v123, v125
	v_add_f32_e32 v0, v90, v0
	s_waitcnt vmcnt(1)
	v_pk_add_f32 v[86:87], v[86:87], v[214:215]
	v_pk_add_f32 v[126:127], v[88:89], v[216:217]
	v_pk_mul_f32 v[88:89], v[86:87], v[86:87]
	v_pk_mul_f32 v[120:121], v[126:127], v[126:127]
	v_cvt_pk_bf16_f32 v86, v86, v87
	v_cvt_pk_bf16_f32 v87, v126, v127
	v_add_f32_e32 v90, v120, v121
	v_add_f32_e32 v88, v88, v89
	global_store_dwordx4 v[132:133], v[122:125], off
	v_add_f32_e32 v88, v88, v90
	v_add_f32_e32 v0, v0, v88
	s_waitcnt vmcnt(1)
	v_pk_add_f32 v[82:83], v[82:83], v[218:219]
	v_pk_add_f32 v[84:85], v[84:85], v[220:221]
	v_pk_mul_f32 v[122:123], v[82:83], v[82:83]
	v_pk_mul_f32 v[124:125], v[84:85], v[84:85]
	v_add_f32_e32 v89, v122, v123
	v_add_f32_e32 v88, v124, v125
	v_add_f32_e32 v88, v89, v88
	v_add_f32_e32 v0, v0, v88
	v_cvt_pk_bf16_f32 v88, v82, v83
	v_cvt_pk_bf16_f32 v89, v84, v85
	s_nop 0
	v_permlane16_swap_b32_e32 v86, v88
	v_permlane16_swap_b32_e32 v87, v89
	v_lshl_add_u64 v[82:83], v[118:119], 0, v[114:115]
	global_store_dwordx4 v[82:83], v[86:89], off
	ds_bpermute_b32 v82, v182, v0
	s_waitcnt lgkmcnt(0)
	v_add_f32_e32 v0, v0, v82
	ds_bpermute_b32 v82, v181, v0
	s_and_saveexec_b64 s[16:17], vcc
	s_cbranch_execz .LBB0_587
	v_ashrrev_i32_e32 v117, 31, v116
	s_waitcnt lgkmcnt(0)
	v_add_f32_e32 v0, v0, v82
	v_lshl_add_u64 v[82:83], v[116:117], 2, s[14:15]
	global_atomic_add_f32 v[82:83], v0, off

; __device__ __forceinline__ unsigned pk2(float lo, float hi) { hwf2 v = {lo, hi}; return __builtin_bit_cast(unsigned, __builtin_convertvector(v, hwbf2)); }
; __device__ __forceinline__ float shfl_lane(float x, int src_lane) { return __int_as_float(__builtin_amdgcn_ds_bpermute(src_lane << 2, __float_as_int(x))); }
; template <int EPI> ...
;     ...
;       _Pragma("unroll") for (int ai = 0; ai < 2; ++ai) _Pragma("unroll") for (int mp = 0; mp < 2; ++mp) {
;         float4 rv[2][2][2];
;         _Pragma("unroll") for (int mi = 0; mi < 2; ++mi) _Pragma("unroll") for (int bj = 0; bj < 2; ++bj) _Pragma("unroll") for (int n = 0; n < 2; ++n)
;           rv[mi][bj][n] = *(const float4*)(residf + (size_t)(brow + ai * HALF + wr * 64 + (mp * 2 + mi) * 16 + fr) * DM + (bcol + bj * HALF + wc * 32 + n * 16 + fq * 4));
;         asm volatile("" ::: "memory");
;         _Pragma("unroll") for (int mi = 0; mi < 2; ++mi) {
;           const int m = mp * 2 + mi;
;           const int row = brow + ai * HALF + wr * 64 + m * 16 + fr;
;           float sq = 0.f;
;           const int coff = (fq & 1) ? 16 + (fq - 1) * 4 : fq * 4;
;           _Pragma("unroll") for (int bj = 0; bj < 2; ++bj) {
;             uint2 pk[2];
;             _Pragma("unroll") for (int n = 0; n < 2; ++n) {
;               const float v0 = rv[mi][bj][n].x + acc[ai][bj][m][n][0], v1 = rv[mi][bj][n].y + acc[ai][bj][m][n][1];
;               const float v2 = rv[mi][bj][n].z + acc[ai][bj][m][n][2], v3 = rv[mi][bj][n].w + acc[ai][bj][m][n][3];
;               sq += (v0 * v0 + v1 * v1) + (v2 * v2 + v3 * v3);
;               pk[n].x = pk2(v0, v1); pk[n].y = pk2(v2, v3);
;             }
;             *(uint4*)(outb + pk_off(row, bcol + bj * HALF + wc * 32 + coff)) = widen_pair(pk[0], pk[1]);
;           }
;           sq += shfl_lane(sq, (te_ & 63) ^ 16); sq += shfl_lane(sq, (te_ & 63) ^ 32);
;           if (fq == 0) atomicAdd(ss_out + row, sq);
.LBB0_589:
	s_or_b64 exec, exec, s[16:17]
	s_waitcnt lgkmcnt(0)
	v_add_u32_e32 v66, 0x80, v152
	v_ashrrev_i32_e32 v67, 31, v66
	v_lshlrev_b64 v[66:67], 14, v[66:67]
	v_lshl_add_u64 v[66:67], s[0:1], 0, v[66:67]
	v_lshl_add_u64 v[94:95], v[66:67], 0, v[154:155]
	v_add_u32_e32 v66, 0x90, v152
	v_ashrrev_i32_e32 v67, 31, v66
	v_lshlrev_b64 v[66:67], 14, v[66:67]
	v_lshl_add_u64 v[66:67], s[0:1], 0, v[66:67]
	v_lshl_add_u64 v[66:67], v[66:67], 0, v[154:155]
	global_load_dwordx4 v[78:81], v[66:67], off
	global_load_dwordx4 v[74:77], v[66:67], off offset:64
	global_load_dwordx4 v[70:73], v[66:67], off offset:512
	s_nop 0
	global_load_dwordx4 v[66:69], v[66:67], off offset:576
	v_add_u32_e32 v83, 0x80, v184
	global_load_dwordx4 v[86:89], v[94:95], off
	global_load_dwordx4 v[222:225], v[94:95], off offset:64
	global_load_dwordx4 v[226:229], v[94:95], off offset:512
	global_load_dwordx4 v[230:233], v[94:95], off offset:576
	v_or_b32_e32 v82, v83, v183
	v_ashrrev_i32_e32 v83, 1, v83
	v_lshlrev_b32_e32 v0, 6, v82
	v_lshlrev_b32_e32 v84, 2, v82
	v_and_b32_e32 v83, 0xffffffc0, v83
	v_and_or_b32 v0, v0, s47, v186
	v_and_b32_e32 v84, 32, v84
	v_bitop3_b32 v0, v0, v187, v84 bitop3:0xde
	v_lshl_add_u64 v[84:85], s[12:13], 0, v[0:1]
	s_waitcnt vmcnt(3)
	v_pk_add_f32 v[86:87], v[62:63], v[86:87]
	v_pk_add_f32 v[88:89], v[64:65], v[88:89]
	v_pk_mul_f32 v[62:63], v[86:87], v[86:87]
	v_pk_mul_f32 v[64:65], v[88:89], v[88:89]
	v_cvt_pk_bf16_f32 v86, v86, v87
	v_cvt_pk_bf16_f32 v87, v88, v89
	s_waitcnt vmcnt(2)
	v_pk_add_f32 v[88:89], v[58:59], v[222:223]
	v_pk_add_f32 v[90:91], v[60:61], v[224:225]
	v_pk_mul_f32 v[58:59], v[88:89], v[88:89]
	v_pk_mul_f32 v[60:61], v[90:91], v[90:91]
	v_cvt_pk_bf16_f32 v88, v88, v89
	v_cvt_pk_bf16_f32 v89, v90, v91
	v_add_u32_e32 v90, v153, v83
	v_ashrrev_i32_e32 v91, 31, v90
	v_lshlrev_b64 v[90:91], 14, v[90:91]
	v_lshl_add_u64 v[96:97], v[84:85], 0, v[90:91]
	v_add_f32_e32 v0, v60, v61
	v_add_f32_e32 v58, v58, v59
	v_add_f32_e32 v0, v58, v0
	v_add_f32_e32 v58, v64, v65
	v_add_f32_e32 v59, v62, v63
	v_add_f32_e32 v58, v59, v58
	v_permlane16_swap_b32_e32 v86, v88
	v_permlane16_swap_b32_e32 v87, v89
	v_add_f32_e32 v0, v58, v0
	s_waitcnt vmcnt(1)
	v_pk_add_f32 v[54:55], v[54:55], v[226:227]
	v_pk_add_f32 v[56:57], v[56:57], v[228:229]
	v_pk_mul_f32 v[98:99], v[54:55], v[54:55]
	v_pk_mul_f32 v[100:101], v[56:57], v[56:57]
	v_add_f32_e32 v59, v98, v99
	v_add_f32_e32 v58, v100, v101
	v_cvt_pk_bf16_f32 v54, v54, v55
	v_cvt_pk_bf16_f32 v55, v56, v57
	global_store_dwordx4 v[96:97], v[86:89], off
	v_add_f32_e32 v58, v59, v58
	v_add_f32_e32 v0, v0, v58
	s_waitcnt vmcnt(1)
	v_pk_add_f32 v[50:51], v[50:51], v[230:231]
	v_pk_add_f32 v[52:53], v[52:53], v[232:233]
	v_pk_mul_f32 v[56:57], v[50:51], v[50:51]
	v_pk_mul_f32 v[86:87], v[52:53], v[52:53]
	v_add_f32_e32 v56, v56, v57
	v_add_f32_e32 v58, v86, v87
	v_add_f32_e32 v56, v56, v58
	v_add_f32_e32 v0, v0, v56
	v_cvt_pk_bf16_f32 v56, v50, v51
	v_add_u32_e32 v50, v140, v83
	v_ashrrev_i32_e32 v51, 31, v50
	v_cvt_pk_bf16_f32 v57, v52, v53
	v_lshlrev_b64 v[50:51], 14, v[50:51]
	v_permlane16_swap_b32_e32 v54, v56
	v_permlane16_swap_b32_e32 v55, v57
	v_lshl_add_u64 v[50:51], v[84:85], 0, v[50:51]
	global_store_dwordx4 v[50:51], v[54:57], off
	ds_bpermute_b32 v50, v182, v0
	s_waitcnt lgkmcnt(0)
	v_add_f32_e32 v0, v0, v50
	ds_bpermute_b32 v50, v181, v0
	s_and_saveexec_b64 s[16:17], vcc
	s_cbranch_execz .LBB0_591
	v_ashrrev_i32_e32 v83, 31, v82
	s_waitcnt lgkmcnt(0)
	v_add_f32_e32 v0, v0, v50
	v_lshl_add_u64 v[50:51], v[82:83], 2, s[14:15]
	global_atomic_add_f32 v[50:51], v0, off

; __device__ __forceinline__ unsigned pk2(float lo, float hi) { hwf2 v = {lo, hi}; return __builtin_bit_cast(unsigned, __builtin_convertvector(v, hwbf2)); }
; __device__ __forceinline__ float shfl_lane(float x, int src_lane) { return __int_as_float(__builtin_amdgcn_ds_bpermute(src_lane << 2, __float_as_int(x))); }
; template <int EPI> ...
;     ...
;       _Pragma("unroll") for (int ai = 0; ai < 2; ++ai) _Pragma("unroll") for (int mp = 0; mp < 2; ++mp) {
;         float4 rv[2][2][2];
;         _Pragma("unroll") for (int mi = 0; mi < 2; ++mi) _Pragma("unroll") for (int bj = 0; bj < 2; ++bj) _Pragma("unroll") for (int n = 0; n < 2; ++n)
;           rv[mi][bj][n] = *(const float4*)(residf + (size_t)(brow + ai * HALF + wr * 64 + (mp * 2 + mi) * 16 + fr) * DM + (bcol + bj * HALF + wc * 32 + n * 16 + fq * 4));
;         asm volatile("" ::: "memory");
;         _Pragma("unroll") for (int mi = 0; mi < 2; ++mi) {
;           const int m = mp * 2 + mi;
;           const int row = brow + ai * HALF + wr * 64 + m * 16 + fr;
;           float sq = 0.f;
;           const int coff = (fq & 1) ? 16 + (fq - 1) * 4 : fq * 4;
;           _Pragma("unroll") for (int bj = 0; bj < 2; ++bj) {
;             uint2 pk[2];
;             _Pragma("unroll") for (int n = 0; n < 2; ++n) {
;               const float v0 = rv[mi][bj][n].x + acc[ai][bj][m][n][0], v1 = rv[mi][bj][n].y + acc[ai][bj][m][n][1];
;               const float v2 = rv[mi][bj][n].z + acc[ai][bj][m][n][2], v3 = rv[mi][bj][n].w + acc[ai][bj][m][n][3];
;               sq += (v0 * v0 + v1 * v1) + (v2 * v2 + v3 * v3);
;               pk[n].x = pk2(v0, v1); pk[n].y = pk2(v2, v3);
;             }
;             *(uint4*)(outb + pk_off(row, bcol + bj * HALF + wc * 32 + coff)) = widen_pair(pk[0], pk[1]);
;           }
;           sq += shfl_lane(sq, (te_ & 63) ^ 16); sq += shfl_lane(sq, (te_ & 63) ^ 32);
;           if (fq == 0) atomicAdd(ss_out + row, sq);
.LBB0_593:
	s_or_b64 exec, exec, s[16:17]
	s_waitcnt lgkmcnt(0)
	v_add_u32_e32 v34, 0xa0, v152
	v_ashrrev_i32_e32 v35, 31, v34
	v_lshlrev_b64 v[34:35], 14, v[34:35]
	v_lshl_add_u64 v[34:35], s[0:1], 0, v[34:35]
	v_lshl_add_u64 v[64:65], v[34:35], 0, v[154:155]
	v_add_u32_e32 v34, 0xb0, v152
	v_ashrrev_i32_e32 v35, 31, v34
	v_lshlrev_b64 v[34:35], 14, v[34:35]
	v_lshl_add_u64 v[34:35], s[0:1], 0, v[34:35]
	v_lshl_add_u64 v[34:35], v[34:35], 0, v[154:155]
	global_load_dwordx4 v[46:49], v[34:35], off
	global_load_dwordx4 v[42:45], v[34:35], off offset:64
	global_load_dwordx4 v[38:41], v[34:35], off offset:512
	s_nop 0
	global_load_dwordx4 v[34:37], v[34:35], off offset:576
	v_add_u32_e32 v51, 0xa0, v184
	global_load_dwordx4 v[54:57], v[64:65], off
	global_load_dwordx4 v[234:237], v[64:65], off offset:64
	global_load_dwordx4 v[238:241], v[64:65], off offset:512
	global_load_dwordx4 v[202:205], v[64:65], off offset:576
	v_or_b32_e32 v50, v51, v183
	v_lshrrev_b32_e32 v0, 3, v51
	v_ashrrev_i32_e32 v51, 1, v51
	v_and_or_b32 v0, v0, 12, v185
	v_lshlrev_b32_e32 v52, 6, v50
	v_lshlrev_b32_e32 v53, 2, v50
	v_and_b32_e32 v51, 0xffffffc0, v51
	v_and_or_b32 v52, v52, s47, v186
	v_lshlrev_b32_e32 v0, 10, v0
	v_and_b32_e32 v53, 32, v53
	v_bitop3_b32 v0, v52, v0, v53 bitop3:0xde
	v_lshl_add_u64 v[52:53], s[12:13], 0, v[0:1]
	s_waitcnt vmcnt(3)
	v_pk_add_f32 v[58:59], v[32:33], v[56:57]
	s_nop 0
	v_pk_mul_f32 v[32:33], v[58:59], v[58:59]
	v_cvt_pk_bf16_f32 v57, v58, v59
	v_pk_add_f32 v[54:55], v[30:31], v[54:55]
	s_waitcnt vmcnt(2)
	v_pk_add_f32 v[60:61], v[28:29], v[236:237]
	v_pk_mul_f32 v[30:31], v[54:55], v[54:55]
	v_cvt_pk_bf16_f32 v56, v54, v55
	v_pk_add_f32 v[54:55], v[26:27], v[234:235]
	v_pk_mul_f32 v[28:29], v[60:61], v[60:61]
	v_cvt_pk_bf16_f32 v59, v60, v61
	v_pk_mul_f32 v[26:27], v[54:55], v[54:55]
	v_cvt_pk_bf16_f32 v58, v54, v55
	v_add_u32_e32 v54, v153, v51
	v_ashrrev_i32_e32 v55, 31, v54
	v_lshlrev_b64 v[54:55], 14, v[54:55]
	v_lshl_add_u64 v[66:67], v[52:53], 0, v[54:55]
	v_add_f32_e32 v0, v28, v29
	v_add_f32_e32 v26, v26, v27
	v_add_f32_e32 v0, v26, v0
	v_add_f32_e32 v26, v32, v33
	v_add_f32_e32 v27, v30, v31
	v_add_f32_e32 v26, v27, v26
	v_permlane16_swap_b32_e32 v56, v58
	v_permlane16_swap_b32_e32 v57, v59
	v_add_f32_e32 v0, v26, v0
	s_waitcnt vmcnt(1)
	v_pk_add_f32 v[22:23], v[22:23], v[238:239]
	v_pk_add_f32 v[60:61], v[24:25], v[240:241]
	v_pk_mul_f32 v[24:25], v[22:23], v[22:23]
	v_pk_mul_f32 v[54:55], v[60:61], v[60:61]
	v_cvt_pk_bf16_f32 v22, v22, v23
	v_cvt_pk_bf16_f32 v23, v60, v61
	v_add_f32_e32 v26, v54, v55
	v_add_f32_e32 v24, v24, v25
	global_store_dwordx4 v[66:67], v[56:59], off
	v_add_f32_e32 v24, v24, v26
	v_add_f32_e32 v0, v0, v24
	s_waitcnt vmcnt(1)
	v_pk_add_f32 v[18:19], v[18:19], v[202:203]
	v_pk_add_f32 v[20:21], v[20:21], v[204:205]
	v_pk_mul_f32 v[56:57], v[18:19], v[18:19]
	v_pk_mul_f32 v[58:59], v[20:21], v[20:21]
	v_add_f32_e32 v25, v56, v57
	v_add_f32_e32 v24, v58, v59
	v_add_f32_e32 v24, v25, v24
	v_add_f32_e32 v0, v0, v24
	v_cvt_pk_bf16_f32 v24, v18, v19
	v_add_u32_e32 v18, v140, v51
	v_ashrrev_i32_e32 v19, 31, v18
	v_cvt_pk_bf16_f32 v25, v20, v21
	v_lshlrev_b64 v[18:19], 14, v[18:19]
	v_permlane16_swap_b32_e32 v22, v24
	v_permlane16_swap_b32_e32 v23, v25
	v_lshl_add_u64 v[18:19], v[52:53], 0, v[18:19]
	global_store_dwordx4 v[18:19], v[22:25], off
	ds_bpermute_b32 v18, v182, v0
	s_waitcnt lgkmcnt(0)
	v_add_f32_e32 v0, v0, v18
	ds_bpermute_b32 v18, v181, v0
	s_and_saveexec_b64 s[16:17], vcc
	s_cbranch_execz .LBB0_595
	v_ashrrev_i32_e32 v51, 31, v50
	s_waitcnt lgkmcnt(0)
	v_add_f32_e32 v0, v0, v18
	v_lshl_add_u64 v[18:19], v[50:51], 2, s[14:15]
	global_atomic_add_f32 v[18:19], v0, off
